# phase A K loop: both operands go memory->LDS with global_load_lds_dwordx4 (swizzle applied on the source chunk), no staging registers, no ds_write ladder
# speedup vs baseline: 1.0052x; 1.0052x over previous
; template <bool ABF, bool BBF, class RowF, class ColF, class Epi>
; __device__ __forceinline__ void gemm_tile(char* smem, int K, RowF rowptr, ColF colptr, int ldb, Epi epi) {
;     ...
;   for (int i = 0; i < NA; i++) ap[i] = (const char*)rowptr(ar0 + ARS * i) + ac * (ABF ? 2 : 4);
;   const int bc = tid & 127, kh = tid >> 7;
;   const float* bp = BBF ? nullptr : ((const float*)colptr(bc) + (size_t)(kh * 32) * ldb);
;   const int br0 = tid >> 3, bcc = (tid & 7) * 8;
;   const char* bq[4];
;   if (BBF) {
; #pragma unroll
;     for (int i = 0; i < 4; i++) bq[i] = (const char*)colptr(br0 + 32 * i) + bcc * 2;
;   }
;   u32x4 ra[NA];
;   float rb[BBF ? 1 : 32];
;   u32x4 rbb[BBF ? 4 : 1];
;   auto gload = [&](int k0) {
; #pragma unroll
;     for (int i = 0; i < NA; i++) ra[i] = *(const u32x4*)(ap[i] + (size_t)k0 * (ABF ? 2 : 4));
;     if (BBF) {
; #pragma unroll
;       for (int i = 0; i < 4; i++) rbb[BBF ? i : 0] = *(const u32x4*)(bq[i] + (size_t)k0 * 2);
;     } else {
;       const float* b = bp + (size_t)k0 * ldb;
; #pragma unroll
;       for (int j = 0; j < 32; j++) rb[BBF ? 0 : j] = b[(size_t)j * ldb];
;     }
;   };
;   auto sstore = [&](int buf) {
;     u16* As = As0 + buf * (GEMM_SMEM / 2);
;     u16* Bs = As + BM * LDT;
; #pragma unroll
;     for (int i = 0; i < NA; i++) {
;       if (ABF) {
;         { const int row = ar0 + ARS * i; *(u32x4*)&As[row * LDT + (((ac >> 3) ^ ((row >> 1) & 7)) << 3)] = ra[i]; }
;       } else {
;         u32x2 v;
;         v[0] = pack2(__uint_as_float(ra[i][0]), __uint_as_float(ra[i][1]));
;         v[1] = pack2(__uint_as_float(ra[i][2]), __uint_as_float(ra[i][3]));
;         { const int row = ar0 + ARS * i; *(u32x2*)&As[row * LDT + (((ac >> 3) ^ ((row >> 1) & 7)) << 3) + (ac & 4)] = v; }
;       }
;     }
;     if (BBF) {
; #pragma unroll
;       for (int i = 0; i < 4; i++) { const int row = br0 + 32 * i; *(u32x4*)&Bs[row * LDT + (((bcc >> 3) ^ ((row >> 1) & 7)) << 3)] = rbb[BBF ? i : 0]; }
;     } else {
; #pragma unroll
;       for (int j = 0; j < 4; j++) {
;         u32x4 v;
;         v[0] = pack2(rb[BBF ? 0 : 8 * j + 0], rb[BBF ? 0 : 8 * j + 1]);
;         v[1] = pack2(rb[BBF ? 0 : 8 * j + 2], rb[BBF ? 0 : 8 * j + 3]);
;         v[2] = pack2(rb[BBF ? 0 : 8 * j + 4], rb[BBF ? 0 : 8 * j + 5]);
;         v[3] = pack2(rb[BBF ? 0 : 8 * j + 6], rb[BBF ? 0 : 8 * j + 7]);
.LBB0_108:
	s_andn2_saveexec_b64 s[0:1], s[0:1]
	s_mov_b32 s2, 0x55555556
	v_mul_hi_i32 v1, v0, s2
	v_lshrrev_b32_e32 v2, 31, v1
	v_add_u32_e32 v1, v1, v2
	v_lshl_add_u32 v2, v1, 1, v1
	v_sub_u32_e32 v0, v0, v2
	v_add_u32_e32 v121, s97, v0
	s_or_b64 exec, exec, s[0:1]
	v_lshrrev_b32_e32 v86, 4, v128
	v_xor_b32_e32 v86, v86, v128
	v_and_b32_e32 v86, 7, v86
	v_lshlrev_b32_e32 v80, 4, v86
	v_mov_b32_e32 v81, 0
	v_sub_u32_e32 v82, v80, v124
	v_lshrrev_b32_e32 v86, 6, v128
	v_ashrrev_i32_e32 v83, 31, v82
	v_readfirstlane_b32 s100, v86
	s_lshl_b32 s100, s100, 10
	v_add_u32_e32 v86, 0x80, v80
	v_mov_b32_e32 v87, 0
	v_lshlrev_b32_e32 v104, 7, v1
	v_ashrrev_i32_e32 v105, 31, v104
	v_lshlrev_b64 v[0:1], 11, v[104:105]
	v_lshl_add_u64 v[2:3], v[98:99], 0, v[0:1]
	v_lshlrev_b32_e32 v137, 7, v121
	v_add_co_u32_e32 v16, vcc, s40, v2
	v_or_b32_e32 v4, v137, v160
	s_nop 0
	v_addc_co_u32_e32 v17, vcc, 0, v3, vcc
	v_min_i32_e32 v10, 0xdef, v4
	v_add_co_u32_e32 v18, vcc, s41, v2
	v_min_i32_e32 v6, 0xe0f, v4
	v_ashrrev_i32_e32 v11, 31, v10
	v_addc_co_u32_e32 v19, vcc, 0, v3, vcc
	v_ashrrev_i32_e32 v7, 31, v6
	v_lshlrev_b64 v[10:11], 11, v[10:11]
	v_min_i32_e32 v12, 0xdcf, v4
	s_add_u32 m0, s100, 0x0
	v_lshl_add_u64 v[84:85], v[2:3], 0, v[82:83]
	global_load_lds_dwordx4 v[84:85], off
	v_add_co_u32_e32 v2, vcc, s42, v2
	v_lshlrev_b64 v[6:7], 11, v[6:7]
	v_lshl_add_u64 v[10:11], v[100:101], 0, v[10:11]
	v_ashrrev_i32_e32 v13, 31, v12
	v_addc_co_u32_e32 v3, vcc, 0, v3, vcc
	v_lshl_add_u64 v[8:9], v[100:101], 0, v[6:7]
	v_lshlrev_b64 v[12:13], 11, v[12:13]
	v_min_i32_e32 v14, 0xdaf, v4
	s_add_u32 m0, s100, 0x1000
	v_lshl_add_u64 v[84:85], v[16:17], 0, v[82:83]
	global_load_lds_dwordx4 v[84:85], off
	s_add_u32 m0, s100, 0x2000
	v_lshl_add_u64 v[84:85], v[18:19], 0, v[82:83]
	global_load_lds_dwordx4 v[84:85], off
	s_add_u32 m0, s100, 0x3000
	v_lshl_add_u64 v[84:85], v[2:3], 0, v[82:83]
	global_load_lds_dwordx4 v[84:85], off
	s_add_u32 m0, s100, 0x4000
	v_lshl_add_u64 v[84:85], v[8:9], 0, v[82:83]
	global_load_lds_dwordx4 v[84:85], off
	v_add_co_u32_e32 v2, vcc, s40, v10
	v_lshl_add_u64 v[12:13], v[100:101], 0, v[12:13]
	v_ashrrev_i32_e32 v15, 31, v14
	v_addc_co_u32_e32 v3, vcc, 0, v11, vcc
	v_lshlrev_b64 v[14:15], 11, v[14:15]
	v_add_co_u32_e32 v8, vcc, s41, v12
	v_lshl_add_u64 v[14:15], v[100:101], 0, v[14:15]
	s_nop 0
	v_addc_co_u32_e32 v9, vcc, 0, v13, vcc
	s_add_u32 m0, s100, 0x5000
	v_lshl_add_u64 v[84:85], v[2:3], 0, v[82:83]
	global_load_lds_dwordx4 v[84:85], off
	s_add_u32 m0, s100, 0x6000
	v_lshl_add_u64 v[84:85], v[8:9], 0, v[82:83]
	global_load_lds_dwordx4 v[84:85], off
	v_add_co_u32_e32 v2, vcc, s42, v14
	s_mov_b64 s[0:1], 0xdef
	s_nop 0
	v_addc_co_u32_e32 v3, vcc, 0, v15, vcc
	s_add_u32 m0, s100, 0x7000
	v_lshl_add_u64 v[84:85], v[2:3], 0, v[82:83]
	global_load_lds_dwordx4 v[84:85], off
	s_mov_b64 s[2:3], 0xdcf
	s_mov_b64 s[6:7], 0xdaf
	v_ashrrev_i32_e32 v5, 31, v4
	v_cmp_gt_i64_e32 vcc, s[0:1], v[4:5]
	v_cmp_gt_i64_e64 s[0:1], s[2:3], v[4:5]
	v_cmp_gt_i64_e64 s[6:7], s[6:7], v[4:5]
	v_lshl_add_u64 v[106:107], v[102:103], 0, v[0:1]
	v_cndmask_b32_e32 v1, 0, v5, vcc
	v_cndmask_b32_e64 v3, 0, v5, s[0:1]
	v_cndmask_b32_e64 v5, 0, v5, s[6:7]
	v_cndmask_b32_e32 v0, v117, v4, vcc
	v_cndmask_b32_e64 v2, v118, v4, s[0:1]
	v_cndmask_b32_e64 v4, v119, v4, s[6:7]
	v_mov_b32_e32 v60, 0
	v_lshlrev_b64 v[0:1], 11, v[0:1]
	v_lshlrev_b64 v[2:3], 11, v[2:3]
	v_lshlrev_b64 v[4:5], 11, v[4:5]
	s_mov_b32 s4, 0
	s_mov_b32 s5, 0
	v_mov_b32_e32 v61, v60
	v_mov_b32_e32 v62, v60
	v_mov_b32_e32 v63, v60
	v_lshl_add_u64 v[108:109], s[24:25], 0, v[6:7]
	v_lshl_add_u64 v[110:111], s[26:27], 0, v[0:1]
	v_lshl_add_u64 v[112:113], s[28:29], 0, v[2:3]
	v_lshl_add_u64 v[114:115], s[30:31], 0, v[4:5]
	v_mov_b32_e32 v56, v60
	v_mov_b32_e32 v57, v60
	v_mov_b32_e32 v58, v60
	v_mov_b32_e32 v59, v60
	v_mov_b32_e32 v52, v60
	v_mov_b32_e32 v53, v60
	v_mov_b32_e32 v54, v60
	v_mov_b32_e32 v55, v60
	v_mov_b32_e32 v48, v60
	v_mov_b32_e32 v49, v60
	v_mov_b32_e32 v50, v60
	v_mov_b32_e32 v51, v60
	v_mov_b32_e32 v44, v60
	v_mov_b32_e32 v45, v60
	v_mov_b32_e32 v46, v60
	v_mov_b32_e32 v47, v60
	v_mov_b32_e32 v40, v60
	v_mov_b32_e32 v41, v60
	v_mov_b32_e32 v42, v60
	v_mov_b32_e32 v43, v60
	v_mov_b32_e32 v36, v60
	v_mov_b32_e32 v37, v60
	v_mov_b32_e32 v38, v60
	v_mov_b32_e32 v39, v60
	v_mov_b32_e32 v32, v60
	v_mov_b32_e32 v33, v60
	v_mov_b32_e32 v34, v60
	v_mov_b32_e32 v35, v60
	v_mov_b32_e32 v28, v60
	v_mov_b32_e32 v29, v60
	v_mov_b32_e32 v30, v60
	v_mov_b32_e32 v31, v60
	v_mov_b32_e32 v24, v60
	v_mov_b32_e32 v25, v60
	v_mov_b32_e32 v26, v60
	v_mov_b32_e32 v27, v60
	v_mov_b32_e32 v20, v60
	v_mov_b32_e32 v21, v60
	v_mov_b32_e32 v22, v60
	v_mov_b32_e32 v23, v60
	v_mov_b32_e32 v16, v60
	v_mov_b32_e32 v17, v60
	v_mov_b32_e32 v18, v60
	v_mov_b32_e32 v19, v60
	v_mov_b32_e32 v12, v60
	v_mov_b32_e32 v13, v60
	v_mov_b32_e32 v14, v60
	v_mov_b32_e32 v15, v60
	v_mov_b32_e32 v8, v60
	v_mov_b32_e32 v9, v60
	v_mov_b32_e32 v10, v60
	v_mov_b32_e32 v11, v60
	v_mov_b32_e32 v4, v60
	v_mov_b32_e32 v5, v60
	v_mov_b32_e32 v6, v60
	v_mov_b32_e32 v7, v60
	v_mov_b32_e32 v0, v60
	v_mov_b32_e32 v1, v60
	v_mov_b32_e32 v2, v60
	v_mov_b32_e32 v3, v60
	s_waitcnt vmcnt(0) lgkmcnt(0)
	s_barrier
	s_mov_b64 s[98:99], 0x10000
	s_branch .LBB0_112
	.p2align 6
; template <bool ABF, bool BBF, class RowF, class ColF, class Epi>
; __device__ __forceinline__ void gemm_tile(char* smem, int K, RowF rowptr, ColF colptr, int ldb, Epi epi) {
;     ...
;   for (int k0 = 0; k0 < K; k0 += BK) {
;     if (k0 + BK < K) gload(k0 + BK);
;     const u16* As = As0 + cur * (GEMM_SMEM / 2);
;     const u16* Bs = As + BM * LDT;
;     {
;       bf16x8 af[2][4], bfr[2][4];
; #pragma unroll
;       for (int ks = 0; ks < 2; ks++) {
; #pragma unroll
;         for (int mi = 0; mi < 4; mi++) af[ks][mi] = *(const bf16x8*)&As[(wm * 64 + mi * 16 + l15) * LDT + (((ks * 4 + kg) ^ swz) << 3)];
; #pragma unroll
;         for (int ni = 0; ni < 4; ni++) bfr[ks][ni] = *(const bf16x8*)&Bs[(wn * 64 + ni * 16 + l15) * LDT + (((ks * 4 + kg) ^ swz) << 3)];
;       }
;       __builtin_amdgcn_sched_barrier(0);
; #pragma unroll
;       for (int ks = 0; ks < 2; ks++)
; #pragma unroll
;         for (int mi = 0; mi < 4; mi++)
; #pragma unroll
;           for (int ni = 0; ni < 4; ni++)
;             acc[mi][ni] = __builtin_amdgcn_mfma_f32_16x16x32_bf16(bfr[ks][ni], af[ks][mi], acc[mi][ni], 0, 0, 0);
;       __builtin_amdgcn_sched_barrier(0);
;     }
;     if (k0 + BK < K) sstore(cur ^ 1);
;     __syncthreads();
.LBB0_112:
.La6_top_X:
	s_xor_b32 s101, s5, 1
	s_lshl_b32 s101, s101, 15
	s_add_u32 s101, s101, s100
	s_cmpk_lt_u32 s4, 0x3c0
	s_cbranch_scc0 .La6_c_X
	s_lshl_b32 s6, s5, 15
	s_add_i32 s6, s6, 0
	v_lshlrev_b32_e32 v96, 1, v163
	v_lshlrev_b32_e32 v105, 1, v164
	v_add3_u32 v139, s6, v96, v105
	v_add3_u32 v141, s6, v105, v96
	ds_read_b128 v[142:145], v139
	ds_read_b128 v[146:149], v141 offset:2048
	ds_read_b128 v[150:153], v141 offset:4096
	ds_read_b128 v[154:157], v141 offset:6144
	v_lshlrev_b32_e32 v139, 1, v162
	v_add_u32_e32 v141, s6, v139
	v_add_u32_e32 v96, v141, v96
	ds_read_b128 v[172:175], v96 offset:16384
	ds_read_b128 v[176:179], v96 offset:18432
	ds_read_b128 v[180:183], v96 offset:20480
	ds_read_b128 v[184:187], v96 offset:22528
	v_lshlrev_b32_e32 v96, 1, v165
	v_add_u32_e32 v158, s6, v96
	v_add_u32_e32 v105, v158, v105
	ds_read_b128 v[188:191], v105
	ds_read_b128 v[192:195], v105 offset:2048
	ds_read_b128 v[196:199], v105 offset:4096
	ds_read_b128 v[200:203], v105 offset:6144
	v_add_u32_e32 v105, v158, v139
	v_add_u32_e32 v96, v141, v96
	ds_read_b128 v[204:207], v105 offset:16384
	ds_read_b128 v[208:211], v96 offset:18432
	ds_read_b128 v[212:215], v96 offset:20480
	ds_read_b128 v[216:219], v96 offset:22528
	s_waitcnt lgkmcnt(11)
	v_mfma_f32_16x16x32_bf16 v[60:63], v[172:175], v[142:145], v[60:63]
	s_add_u32 m0, s101, 0x0
	v_lshl_add_u64 v[242:243], v[106:107], 0, v[86:87]
	global_load_lds_dwordx4 v[242:243], off
	s_waitcnt lgkmcnt(10)
	v_mfma_f32_16x16x32_bf16 v[56:59], v[176:179], v[142:145], v[56:59]
	s_add_u32 m0, s101, 0x1000
	v_lshl_add_u64 v[242:243], v[242:243], 0, s[98:99]
	global_load_lds_dwordx4 v[242:243], off
	s_waitcnt lgkmcnt(9)
	v_mfma_f32_16x16x32_bf16 v[52:55], v[180:183], v[142:145], v[52:55]
	s_add_u32 m0, s101, 0x2000
	v_lshl_add_u64 v[242:243], v[242:243], 0, s[98:99]
	global_load_lds_dwordx4 v[242:243], off
	s_waitcnt lgkmcnt(8)
	v_mfma_f32_16x16x32_bf16 v[48:51], v[184:187], v[142:145], v[48:51]
	s_add_u32 m0, s101, 0x3000
	v_lshl_add_u64 v[242:243], v[242:243], 0, s[98:99]
	global_load_lds_dwordx4 v[242:243], off
	v_mfma_f32_16x16x32_bf16 v[44:47], v[172:175], v[146:149], v[44:47]
	s_add_u32 m0, s101, 0x4000
	v_lshl_add_u64 v[84:85], v[108:109], 0, v[80:81]
	global_load_lds_dwordx4 v[84:85], off
	v_mfma_f32_16x16x32_bf16 v[40:43], v[176:179], v[146:149], v[40:43]
	s_add_u32 m0, s101, 0x5000
	v_lshl_add_u64 v[84:85], v[110:111], 0, v[80:81]
	global_load_lds_dwordx4 v[84:85], off
	v_mfma_f32_16x16x32_bf16 v[36:39], v[180:183], v[146:149], v[36:39]
	s_add_u32 m0, s101, 0x6000
	v_lshl_add_u64 v[84:85], v[112:113], 0, v[80:81]
	global_load_lds_dwordx4 v[84:85], off
	v_mfma_f32_16x16x32_bf16 v[32:35], v[184:187], v[146:149], v[32:35]
	s_add_u32 m0, s101, 0x7000
	v_lshl_add_u64 v[84:85], v[114:115], 0, v[80:81]
	global_load_lds_dwordx4 v[84:85], off
	v_mfma_f32_16x16x32_bf16 v[28:31], v[172:175], v[150:153], v[28:31]
	v_mfma_f32_16x16x32_bf16 v[24:27], v[176:179], v[150:153], v[24:27]
	v_mfma_f32_16x16x32_bf16 v[20:23], v[180:183], v[150:153], v[20:23]
	v_mfma_f32_16x16x32_bf16 v[16:19], v[184:187], v[150:153], v[16:19]
	v_mfma_f32_16x16x32_bf16 v[12:15], v[172:175], v[154:157], v[12:15]
	v_mfma_f32_16x16x32_bf16 v[8:11], v[176:179], v[154:157], v[8:11]
	v_mfma_f32_16x16x32_bf16 v[4:7], v[180:183], v[154:157], v[4:7]
	v_mfma_f32_16x16x32_bf16 v[0:3], v[184:187], v[154:157], v[0:3]
	s_waitcnt lgkmcnt(3)
	v_mfma_f32_16x16x32_bf16 v[60:63], v[204:207], v[188:191], v[60:63]
	s_waitcnt lgkmcnt(2)
	v_mfma_f32_16x16x32_bf16 v[56:59], v[208:211], v[188:191], v[56:59]
	s_waitcnt lgkmcnt(1)
	v_mfma_f32_16x16x32_bf16 v[52:55], v[212:215], v[188:191], v[52:55]
	s_waitcnt lgkmcnt(0)
	v_mfma_f32_16x16x32_bf16 v[48:51], v[216:219], v[188:191], v[48:51]
	v_mfma_f32_16x16x32_bf16 v[44:47], v[204:207], v[192:195], v[44:47]
	v_mfma_f32_16x16x32_bf16 v[40:43], v[208:211], v[192:195], v[40:43]
	v_mfma_f32_16x16x32_bf16 v[36:39], v[212:215], v[192:195], v[36:39]
	v_mfma_f32_16x16x32_bf16 v[32:35], v[216:219], v[192:195], v[32:35]
	v_mfma_f32_16x16x32_bf16 v[28:31], v[204:207], v[196:199], v[28:31]
	v_mfma_f32_16x16x32_bf16 v[24:27], v[208:211], v[196:199], v[24:27]
	v_mfma_f32_16x16x32_bf16 v[20:23], v[212:215], v[196:199], v[20:23]
	v_mfma_f32_16x16x32_bf16 v[16:19], v[216:219], v[196:199], v[16:19]
	v_mfma_f32_16x16x32_bf16 v[12:15], v[204:207], v[200:203], v[12:15]
	v_mfma_f32_16x16x32_bf16 v[8:11], v[208:211], v[200:203], v[8:11]
	v_mfma_f32_16x16x32_bf16 v[4:7], v[212:215], v[200:203], v[4:7]
	v_mfma_f32_16x16x32_bf16 v[0:3], v[216:219], v[200:203], v[0:3]
	s_waitcnt vmcnt(0)
	s_branch .La6_e_X
; template <bool ABF, bool BBF, class RowF, class ColF, class Epi>
; __device__ __forceinline__ void gemm_tile(char* smem, int K, RowF rowptr, ColF colptr, int ldb, Epi epi) {
;     ...
;   for (int k0 = 0; k0 < K; k0 += BK) {
;     if (k0 + BK < K) gload(k0 + BK);
;     const u16* As = As0 + cur * (GEMM_SMEM / 2);
;     const u16* Bs = As + BM * LDT;
;     {
;       bf16x8 af[2][4], bfr[2][4];
; #pragma unroll
;       for (int ks = 0; ks < 2; ks++) {
; #pragma unroll
;         for (int mi = 0; mi < 4; mi++) af[ks][mi] = *(const bf16x8*)&As[(wm * 64 + mi * 16 + l15) * LDT + (((ks * 4 + kg) ^ swz) << 3)];
; #pragma unroll
;         for (int ni = 0; ni < 4; ni++) bfr[ks][ni] = *(const bf16x8*)&Bs[(wn * 64 + ni * 16 + l15) * LDT + (((ks * 4 + kg) ^ swz) << 3)];
;       }
;       __builtin_amdgcn_sched_barrier(0);
; #pragma unroll
;       for (int ks = 0; ks < 2; ks++)
; #pragma unroll
;         for (int mi = 0; mi < 4; mi++)
; #pragma unroll
;           for (int ni = 0; ni < 4; ni++)
;             acc[mi][ni] = __builtin_amdgcn_mfma_f32_16x16x32_bf16(bfr[ks][ni], af[ks][mi], acc[mi][ni], 0, 0, 0);
;       __builtin_amdgcn_sched_barrier(0);
;     }
;     if (k0 + BK < K) sstore(cur ^ 1);
;     __syncthreads();
;     cur ^= 1;
;   }
.La6_c_X:
	s_lshl_b32 s6, s5, 15
	s_add_i32 s6, s6, 0
	v_lshlrev_b32_e32 v96, 1, v163
	v_lshlrev_b32_e32 v105, 1, v164
	v_add3_u32 v139, s6, v96, v105
	v_add3_u32 v141, s6, v105, v96
	ds_read_b128 v[142:145], v139
	ds_read_b128 v[146:149], v141 offset:2048
	ds_read_b128 v[150:153], v141 offset:4096
	ds_read_b128 v[154:157], v141 offset:6144
	v_lshlrev_b32_e32 v139, 1, v162
	v_add_u32_e32 v141, s6, v139
	v_add_u32_e32 v96, v141, v96
	ds_read_b128 v[172:175], v96 offset:16384
	ds_read_b128 v[176:179], v96 offset:18432
	ds_read_b128 v[180:183], v96 offset:20480
	ds_read_b128 v[184:187], v96 offset:22528
	v_lshlrev_b32_e32 v96, 1, v165
	v_add_u32_e32 v158, s6, v96
	v_add_u32_e32 v105, v158, v105
	ds_read_b128 v[188:191], v105
	ds_read_b128 v[192:195], v105 offset:2048
	ds_read_b128 v[196:199], v105 offset:4096
	ds_read_b128 v[200:203], v105 offset:6144
	v_add_u32_e32 v105, v158, v139
	v_add_u32_e32 v96, v141, v96
	ds_read_b128 v[204:207], v105 offset:16384
	ds_read_b128 v[208:211], v96 offset:18432
	ds_read_b128 v[212:215], v96 offset:20480
	ds_read_b128 v[216:219], v96 offset:22528
	s_waitcnt lgkmcnt(11)
	v_mfma_f32_16x16x32_bf16 v[60:63], v[172:175], v[142:145], v[60:63]
	s_waitcnt lgkmcnt(10)
	v_mfma_f32_16x16x32_bf16 v[56:59], v[176:179], v[142:145], v[56:59]
	s_waitcnt lgkmcnt(9)
	v_mfma_f32_16x16x32_bf16 v[52:55], v[180:183], v[142:145], v[52:55]
	s_waitcnt lgkmcnt(8)
	v_mfma_f32_16x16x32_bf16 v[48:51], v[184:187], v[142:145], v[48:51]
	v_mfma_f32_16x16x32_bf16 v[44:47], v[172:175], v[146:149], v[44:47]
	v_mfma_f32_16x16x32_bf16 v[40:43], v[176:179], v[146:149], v[40:43]
	v_mfma_f32_16x16x32_bf16 v[36:39], v[180:183], v[146:149], v[36:39]
	v_mfma_f32_16x16x32_bf16 v[32:35], v[184:187], v[146:149], v[32:35]
	v_mfma_f32_16x16x32_bf16 v[28:31], v[172:175], v[150:153], v[28:31]
	v_mfma_f32_16x16x32_bf16 v[24:27], v[176:179], v[150:153], v[24:27]
	v_mfma_f32_16x16x32_bf16 v[20:23], v[180:183], v[150:153], v[20:23]
	v_mfma_f32_16x16x32_bf16 v[16:19], v[184:187], v[150:153], v[16:19]
	v_mfma_f32_16x16x32_bf16 v[12:15], v[172:175], v[154:157], v[12:15]
	v_mfma_f32_16x16x32_bf16 v[8:11], v[176:179], v[154:157], v[8:11]
	v_mfma_f32_16x16x32_bf16 v[4:7], v[180:183], v[154:157], v[4:7]
	v_mfma_f32_16x16x32_bf16 v[0:3], v[184:187], v[154:157], v[0:3]
	s_waitcnt lgkmcnt(3)
	v_mfma_f32_16x16x32_bf16 v[60:63], v[204:207], v[188:191], v[60:63]
	s_waitcnt lgkmcnt(2)
	v_mfma_f32_16x16x32_bf16 v[56:59], v[208:211], v[188:191], v[56:59]
	s_waitcnt lgkmcnt(1)
	v_mfma_f32_16x16x32_bf16 v[52:55], v[212:215], v[188:191], v[52:55]
	s_waitcnt lgkmcnt(0)
	v_mfma_f32_16x16x32_bf16 v[48:51], v[216:219], v[188:191], v[48:51]
	v_mfma_f32_16x16x32_bf16 v[44:47], v[204:207], v[192:195], v[44:47]
	v_mfma_f32_16x16x32_bf16 v[40:43], v[208:211], v[192:195], v[40:43]
	v_mfma_f32_16x16x32_bf16 v[36:39], v[212:215], v[192:195], v[36:39]
	v_mfma_f32_16x16x32_bf16 v[32:35], v[216:219], v[192:195], v[32:35]
	v_mfma_f32_16x16x32_bf16 v[28:31], v[204:207], v[196:199], v[28:31]
	v_mfma_f32_16x16x32_bf16 v[24:27], v[208:211], v[196:199], v[24:27]
	v_mfma_f32_16x16x32_bf16 v[20:23], v[212:215], v[196:199], v[20:23]
	v_mfma_f32_16x16x32_bf16 v[16:19], v[216:219], v[196:199], v[16:19]
	v_mfma_f32_16x16x32_bf16 v[12:15], v[204:207], v[200:203], v[12:15]
	v_mfma_f32_16x16x32_bf16 v[8:11], v[208:211], v[200:203], v[8:11]
	v_mfma_f32_16x16x32_bf16 v[4:7], v[212:215], v[200:203], v[4:7]
	v_mfma_f32_16x16x32_bf16 v[0:3], v[216:219], v[200:203], v[0:3]
.La6_e_X:
	s_add_i32 s4, s4, 64
	s_xor_b32 s5, s5, 1
	v_lshl_add_u64 v[106:107], v[106:107], 0, s[22:23]
	v_lshl_add_u64 v[108:109], v[108:109], 0, s[22:23]
	v_lshl_add_u64 v[110:111], v[110:111], 0, s[22:23]
	v_lshl_add_u64 v[112:113], v[112:113], 0, s[22:23]
	v_lshl_add_u64 v[114:115], v[114:115], 0, s[22:23]
	s_waitcnt lgkmcnt(0)
	s_barrier
	s_cmpk_lt_u32 s4, 0x400
	s_cbranch_scc1 .La6_top_X
